# conversion item loop prefetch fix applied to the layer-0 in-projection tail and the two FFN-up idle-half-round instances as well
# speedup vs baseline: 1.0007x; 1.0007x over previous
; #define LAS __attribute__((address_space(3)))
; __device__ __forceinline__ void p0_item_process(const PItem& it, int lane, const f32x4 (&v)[8], LAS float* scr) {
;     LAS float* gl = scr + 64 * 36 + 32; LAS float* bl = gl + 64;
;     ...
; #pragma unroll
;     for (int i = 0; i < 8; ++i) *(LAS f32x4*)(scr + SCR_ROW(8 * i + (lane >> 3)) + 4 * (lane & 7)) = v[i];
;     gl[lane] = it.g ? it.g[it.k0 + lane] : 1.f; bl[lane] = it.be ? it.be[it.k0 + lane] : 0.f;
; __device__ __forceinline__ void p0_convert(const Frame& F, const Args& a, int it_lo, int it_hi, int widx, int nw, LAS float* scr) {
;     ...
;         for (int it = it0; it < itend; it += nw) {
;             const bool more = it + nw < itend;
;             PItem nxt = cur; f32x4 vn[8];
;             if (more) { nxt = p0_decode(a, it + nw); p0_item_load(nxt, F.lane, vn); }
;             p0_item_process(cur, F.lane, vc, scr);
.LBB0_472:
	v_add_u32_e32 v232, s16, v67
	v_ashrrev_i32_e32 v233, 31, v232
	v_mov_b32_e32 v230, 1.0
	v_mov_b32_e32 v231, 0
	s_cmp_eq_u64 s[24:25], 0
	s_cbranch_scc1 .Lcv_ng_ip0
	v_lshl_add_u64 v[234:235], v[232:233], 2, s[24:25]
	global_load_dword v230, v[234:235], off
.Lcv_ng_ip0:
	s_cmp_eq_u64 s[64:65], 0
	s_cbranch_scc1 .Lcv_nb_ip0
	v_lshl_add_u64 v[234:235], v[232:233], 2, s[64:65]
	global_load_dword v231, v[234:235], off

; #define LAS __attribute__((address_space(3)))
; #define LDS_WAIT() asm volatile("s_waitcnt lgkmcnt(0)" ::: "memory")
; __device__ __forceinline__ void p0_item_process(const PItem& it, int lane, const f32x4 (&v)[8], LAS float* scr) {
;     LAS float* gl = scr + 64 * 36 + 32; LAS float* bl = gl + 64;
;     ...
; #pragma unroll
;     for (int i = 0; i < 8; ++i) *(LAS f32x4*)(scr + SCR_ROW(8 * i + (lane >> 3)) + 4 * (lane & 7)) = v[i];
;     gl[lane] = it.g ? it.g[it.k0 + lane] : 1.f; bl[lane] = it.be ? it.be[it.k0 + lane] : 0.f;
;     LDS_WAIT(); asm volatile("" ::: "memory");
.LBB0_490:
	s_waitcnt vmcnt(15)
	ds_write_b128 v78, v[58:61]
	s_waitcnt vmcnt(14)
	ds_write_b128 v79, v[42:45] offset:16
	s_waitcnt vmcnt(13)
	ds_write_b128 v80, v[54:57] offset:32
	s_waitcnt vmcnt(12)
	ds_write_b128 v81, v[38:41] offset:48
	s_waitcnt vmcnt(11)
	ds_write_b128 v82, v[50:53] offset:64
	s_waitcnt vmcnt(10)
	ds_write_b128 v83, v[34:37] offset:80
	s_waitcnt vmcnt(9)
	ds_write_b128 v84, v[46:49] offset:96
	s_waitcnt vmcnt(8)
	ds_write_b128 v85, v[62:65] offset:112
	s_cmp_lg_u64 s[64:65], 0
	s_cselect_b64 s[24:25], -1, 0
	s_waitcnt vmcnt(8)
	ds_write_b32 v86, v230 offset:9344
	ds_write_b32 v86, v231 offset:9600
	s_waitcnt lgkmcnt(0)
	s_cmp_eq_u64 s[20:21], 0
	s_cbranch_scc1 .LBB0_503
	v_mov_b32_e32 v34, 0
	s_mov_b32 s0, 0
	v_mov_b32_e32 v36, v90
	v_mov_b32_e32 v35, v34

; #define LAS __attribute__((address_space(3)))
; #define LDS_WAIT() asm volatile("s_waitcnt lgkmcnt(0)" ::: "memory")
; __device__ __forceinline__ unsigned pk2(float lo, float hi) { const f32x2_cv v = {lo, hi}; const bf16x2_cv b = __builtin_convertvector(v, bf16x2_cv); return __builtin_bit_cast(unsigned, b); }
; __device__ __forceinline__ void st16_wt(void* p, f32x4 v) { asm volatile("global_store_dwordx4 %0, %1, off sc1\n\ts_nop 1" :: "v"(p), "v"(v) : "memory"); }
; __device__ __forceinline__ void p0_item_process(const PItem& it, int lane, const f32x4 (&v)[8], LAS float* scr) {
;     ...
;     const int c = lane & 7;
;     const f32x4 g0 = *(const LAS f32x4*)(gl + 8 * c), g1 = *(const LAS f32x4*)(gl + 8 * c + 4);
; #pragma unroll
;     for (int j = 0; j < 4; ++j) { const int n = (lane >> 3) + 8 * j; const LAS float* sp = scr + SCR_ROW(8 * c) + n;
;         v4u o; o.x = pk2(sp[0 * 36] * g0[0], sp[1 * 36] * g0[1]); o.y = pk2(sp[2 * 36] * g0[2], sp[3 * 36] * g0[3]); o.z = pk2(sp[4 * 36] * g1[0], sp[5 * 36] * g1[1]); o.w = pk2(sp[6 * 36] * g1[2], sp[7 * 36] * g1[3]);
;         st16_wt((void*)(it.WT + (size_t)(it.drow0 + n) * it.K + it.k0 + 8 * c), __builtin_bit_cast(f32x4, o)); }
;     LDS_WAIT(); asm volatile("" ::: "memory");
; __device__ __forceinline__ void p0_convert(const Frame& F, const Args& a, int it_lo, int it_hi, int widx, int nw, LAS float* scr) {
;     ...
;             if (more) { cur = nxt;
; #pragma unroll
;                 for (int i = 0; i < 8; ++i) vc[i] = vn[i]; }
.LBB0_503:
	ds_read2_b32 v[42:43], v88 offset1:36
	s_waitcnt lgkmcnt(1)
	ds_read_b128 v[34:37], v87 offset:9344
	ds_read_b128 v[38:41], v87 offset:9360
	ds_read2_b32 v[44:45], v88 offset0:72 offset1:108
	ds_read2_b32 v[46:47], v88 offset0:144 offset1:180
	ds_read2_b32 v[48:49], v88 offset0:216 offset1:252
	s_waitcnt lgkmcnt(4)
	v_pk_mul_f32 v[42:43], v[34:35], v[42:43]
	s_ashr_i32 s17, s16, 31
	s_waitcnt lgkmcnt(2)
	v_pk_mul_f32 v[44:45], v[36:37], v[44:45]
	v_cvt_pk_bf16_f32 v42, v42, v43
	v_cvt_pk_bf16_f32 v43, v44, v45
	s_waitcnt lgkmcnt(1)
	v_pk_mul_f32 v[44:45], v[38:39], v[46:47]
	s_waitcnt lgkmcnt(0)
	v_pk_mul_f32 v[46:47], v[40:41], v[48:49]
	v_cvt_pk_bf16_f32 v44, v44, v45
	v_cvt_pk_bf16_f32 v45, v46, v47
	v_add_u32_e32 v46, s14, v70
	v_ashrrev_i32_e32 v49, 31, v46
	v_mad_u64_u32 v[46:47], s[0:1], v46, s2, 0
	v_mov_b32_e32 v48, v47
	v_mad_u64_u32 v[48:49], s[0:1], v49, s2, v[48:49]
	v_mov_b32_e32 v47, v48
	v_lshl_add_u64 v[46:47], v[46:47], 1, s[12:13]
	s_lshl_b64 s[16:17], s[16:17], 1
	v_lshl_add_u64 v[46:47], v[46:47], 0, s[16:17]
	v_lshl_add_u64 v[46:47], v[46:47], 0, v[0:1]
	global_store_dwordx4 v[46:47], v[42:45], off sc1
	s_nop 1
	ds_read2_b32 v[42:43], v88 offset0:8 offset1:44
	ds_read2_b32 v[44:45], v88 offset0:80 offset1:116
	v_add_u32_e32 v50, 0x200, v88
	ds_read2_b32 v[46:47], v88 offset0:152 offset1:188
	ds_read2_b32 v[48:49], v50 offset0:96 offset1:132
	s_waitcnt lgkmcnt(3)
	v_pk_mul_f32 v[42:43], v[34:35], v[42:43]
	s_waitcnt lgkmcnt(2)
	v_pk_mul_f32 v[44:45], v[36:37], v[44:45]
	v_cvt_pk_bf16_f32 v42, v42, v43
	v_cvt_pk_bf16_f32 v43, v44, v45
	s_waitcnt lgkmcnt(1)
	v_pk_mul_f32 v[44:45], v[38:39], v[46:47]
	s_waitcnt lgkmcnt(0)
	v_pk_mul_f32 v[46:47], v[40:41], v[48:49]
	v_cvt_pk_bf16_f32 v44, v44, v45
	v_cvt_pk_bf16_f32 v45, v46, v47
	v_add_u32_e32 v46, s14, v71
	v_ashrrev_i32_e32 v49, 31, v46
	v_mad_u64_u32 v[46:47], s[0:1], v46, s2, 0
	v_mov_b32_e32 v48, v47
	v_mad_u64_u32 v[48:49], s[0:1], v49, s2, v[48:49]
	v_mov_b32_e32 v47, v48
	v_lshl_add_u64 v[46:47], v[46:47], 1, s[12:13]
	v_lshl_add_u64 v[46:47], v[46:47], 0, s[16:17]
	v_lshl_add_u64 v[46:47], v[46:47], 0, v[0:1]
	global_store_dwordx4 v[46:47], v[42:45], off sc1
	s_nop 1
	ds_read2_b32 v[42:43], v88 offset0:16 offset1:52
	ds_read2_b32 v[44:45], v88 offset0:88 offset1:124
	ds_read2_b32 v[46:47], v88 offset0:160 offset1:196
	ds_read2_b32 v[48:49], v50 offset0:104 offset1:140
	s_andn2_b64 vcc, exec, s[30:31]
	s_waitcnt lgkmcnt(3)
	v_pk_mul_f32 v[42:43], v[34:35], v[42:43]
	s_waitcnt lgkmcnt(2)
	v_pk_mul_f32 v[44:45], v[36:37], v[44:45]
	v_cvt_pk_bf16_f32 v42, v42, v43
	v_cvt_pk_bf16_f32 v43, v44, v45
	s_waitcnt lgkmcnt(1)
	v_pk_mul_f32 v[44:45], v[38:39], v[46:47]
	s_waitcnt lgkmcnt(0)
	v_pk_mul_f32 v[46:47], v[40:41], v[48:49]
	v_cvt_pk_bf16_f32 v44, v44, v45
	v_cvt_pk_bf16_f32 v45, v46, v47
	v_add_u32_e32 v46, s14, v72
	v_ashrrev_i32_e32 v49, 31, v46
	v_mad_u64_u32 v[46:47], s[0:1], v46, s2, 0
	v_mov_b32_e32 v48, v47
	v_mad_u64_u32 v[48:49], s[0:1], v49, s2, v[48:49]
	v_mov_b32_e32 v47, v48
	v_lshl_add_u64 v[46:47], v[46:47], 1, s[12:13]
	v_lshl_add_u64 v[46:47], v[46:47], 0, s[16:17]
	v_lshl_add_u64 v[46:47], v[46:47], 0, v[0:1]
	global_store_dwordx4 v[46:47], v[42:45], off sc1
	s_nop 1
	ds_read2_b32 v[42:43], v88 offset0:24 offset1:60
	ds_read2_b32 v[44:45], v88 offset0:96 offset1:132
	ds_read2_b32 v[46:47], v50 offset0:112 offset1:148
	s_waitcnt lgkmcnt(2)
	v_pk_mul_f32 v[34:35], v[34:35], v[42:43]
	ds_read2_b32 v[42:43], v88 offset0:168 offset1:204
	s_waitcnt lgkmcnt(2)
	v_pk_mul_f32 v[36:37], v[36:37], v[44:45]
	v_cvt_pk_bf16_f32 v34, v34, v35
	v_cvt_pk_bf16_f32 v35, v36, v37
	s_waitcnt lgkmcnt(0)
	v_pk_mul_f32 v[36:37], v[38:39], v[42:43]
	v_pk_mul_f32 v[38:39], v[40:41], v[46:47]
	v_cvt_pk_bf16_f32 v36, v36, v37
	v_cvt_pk_bf16_f32 v37, v38, v39
	v_add_u32_e32 v38, s14, v73
	v_ashrrev_i32_e32 v41, 31, v38
	v_mad_u64_u32 v[38:39], s[0:1], v38, s2, 0
	v_mov_b32_e32 v40, v39
	v_mad_u64_u32 v[40:41], s[0:1], v41, s2, v[40:41]
	v_mov_b32_e32 v39, v40
	v_lshl_add_u64 v[38:39], v[38:39], 1, s[12:13]
	v_lshl_add_u64 v[38:39], v[38:39], 0, s[16:17]
	v_lshl_add_u64 v[38:39], v[38:39], 0, v[0:1]
	global_store_dwordx4 v[38:39], v[34:37], off sc1
	s_nop 1
	s_waitcnt lgkmcnt(0)
	s_mov_b64 s[12:13], -1
	s_cbranch_vccnz .LBB0_471
	s_waitcnt vmcnt(4)
	s_mov_b64 s[12:13], 0
	v_mov_b32_e32 v49, v33
	v_mov_b32_e32 v48, v32
	v_mov_b32_e32 v47, v31
	v_mov_b32_e32 v46, v30
	v_mov_b32_e32 v37, v21
	v_mov_b32_e32 v36, v20
	v_mov_b32_e32 v35, v19
	v_mov_b32_e32 v34, v18
	v_mov_b32_e32 v53, v25
	v_mov_b32_e32 v52, v24
	v_mov_b32_e32 v51, v23
	v_mov_b32_e32 v50, v22
	v_mov_b32_e32 v41, v13
	v_mov_b32_e32 v40, v12
	v_mov_b32_e32 v39, v11
	v_mov_b32_e32 v38, v10
	v_mov_b32_e32 v57, v17
	v_mov_b32_e32 v56, v16
	v_mov_b32_e32 v55, v15
	v_mov_b32_e32 v54, v14
	v_mov_b32_e32 v45, v5
	v_mov_b32_e32 v44, v4
	v_mov_b32_e32 v43, v3
	v_mov_b32_e32 v42, v2
	v_mov_b32_e32 v61, v9
	v_mov_b32_e32 v60, v8
	v_mov_b32_e32 v59, v7
	v_mov_b32_e32 v58, v6
	s_branch .LBB0_471
.Lcv_np_ip0:
	s_waitcnt vmcnt(0)
	s_branch .LBB0_490
.LBB0_505:
	s_movk_i32 s40, 0xb00
	s_mov_b64 s[62:63], 0x400
	s_mov_b64 s[26:27], 0
	s_mov_b64 s[88:89], 0
	s_mov_b64 s[28:29], 0
	s_mov_b32 s48, s41
	s_mov_b64 s[34:35], 0
	s_andn2_b64 vcc, exec, s[86:87]
	s_cbranch_vccz .LBB0_480
	s_branch .LBB0_481

; #define LAS __attribute__((address_space(3)))
; __device__ __forceinline__ void p0_item_process(const PItem& it, int lane, const f32x4 (&v)[8], LAS float* scr) {
;     LAS float* gl = scr + 64 * 36 + 32; LAS float* bl = gl + 64;
;     ...
; #pragma unroll
;     for (int i = 0; i < 8; ++i) *(LAS f32x4*)(scr + SCR_ROW(8 * i + (lane >> 3)) + 4 * (lane & 7)) = v[i];
;     gl[lane] = it.g ? it.g[it.k0 + lane] : 1.f; bl[lane] = it.be ? it.be[it.k0 + lane] : 0.f;
.LBB0_1260:
	v_add_u32_e32 v232, s16, v67
	v_ashrrev_i32_e32 v233, 31, v232
	v_mov_b32_e32 v230, 1.0
	v_mov_b32_e32 v231, 0
	s_cmp_eq_u64 s[86:87], 0
	s_cbranch_scc1 .Lcv_ng_fu0
	v_lshl_add_u64 v[234:235], v[232:233], 2, s[86:87]
	global_load_dword v230, v[234:235], off

; #define LAS __attribute__((address_space(3)))
; #define LDS_WAIT() asm volatile("s_waitcnt lgkmcnt(0)" ::: "memory")
; __device__ __forceinline__ void p0_item_process(const PItem& it, int lane, const f32x4 (&v)[8], LAS float* scr) {
;     LAS float* gl = scr + 64 * 36 + 32; LAS float* bl = gl + 64;
;     ...
; #pragma unroll
;     for (int i = 0; i < 8; ++i) *(LAS f32x4*)(scr + SCR_ROW(8 * i + (lane >> 3)) + 4 * (lane & 7)) = v[i];
;     gl[lane] = it.g ? it.g[it.k0 + lane] : 1.f; bl[lane] = it.be ? it.be[it.k0 + lane] : 0.f;
;     LDS_WAIT(); asm volatile("" ::: "memory");
.LBB0_1278:
	s_waitcnt vmcnt(15)
	ds_write_b128 v78, v[58:61]
	s_waitcnt vmcnt(14)
	ds_write_b128 v79, v[42:45] offset:16
	s_waitcnt vmcnt(13)
	ds_write_b128 v80, v[54:57] offset:32
	s_waitcnt vmcnt(12)
	ds_write_b128 v81, v[38:41] offset:48
	s_waitcnt vmcnt(11)
	ds_write_b128 v82, v[50:53] offset:64
	s_waitcnt vmcnt(10)
	ds_write_b128 v83, v[34:37] offset:80
	s_waitcnt vmcnt(9)
	ds_write_b128 v84, v[46:49] offset:96
	s_waitcnt vmcnt(8)
	ds_write_b128 v85, v[62:65] offset:112
	s_cmp_lg_u64 s[64:65], 0
	s_cselect_b64 s[86:87], -1, 0
	s_waitcnt vmcnt(8)
	ds_write_b32 v86, v230 offset:9344
	ds_write_b32 v86, v231 offset:9600
	s_waitcnt lgkmcnt(0)
	s_cmp_eq_u64 s[20:21], 0
	s_cbranch_scc1 .LBB0_1291
	v_mov_b32_e32 v34, 0
	s_mov_b32 s0, 0
	v_mov_b32_e32 v36, v90
	v_mov_b32_e32 v35, v34

; #define LAS __attribute__((address_space(3)))
; #define LDS_WAIT() asm volatile("s_waitcnt lgkmcnt(0)" ::: "memory")
; __device__ __forceinline__ unsigned pk2(float lo, float hi) { const f32x2_cv v = {lo, hi}; const bf16x2_cv b = __builtin_convertvector(v, bf16x2_cv); return __builtin_bit_cast(unsigned, b); }
; __device__ __forceinline__ void st16_wt(void* p, f32x4 v) { asm volatile("global_store_dwordx4 %0, %1, off sc1\n\ts_nop 1" :: "v"(p), "v"(v) : "memory"); }
; __device__ __forceinline__ void p0_item_process(const PItem& it, int lane, const f32x4 (&v)[8], LAS float* scr) {
;     ...
;     const int c = lane & 7;
;     const f32x4 g0 = *(const LAS f32x4*)(gl + 8 * c), g1 = *(const LAS f32x4*)(gl + 8 * c + 4);
; #pragma unroll
;     for (int j = 0; j < 4; ++j) { const int n = (lane >> 3) + 8 * j; const LAS float* sp = scr + SCR_ROW(8 * c) + n;
;         v4u o; o.x = pk2(sp[0 * 36] * g0[0], sp[1 * 36] * g0[1]); o.y = pk2(sp[2 * 36] * g0[2], sp[3 * 36] * g0[3]); o.z = pk2(sp[4 * 36] * g1[0], sp[5 * 36] * g1[1]); o.w = pk2(sp[6 * 36] * g1[2], sp[7 * 36] * g1[3]);
;         st16_wt((void*)(it.WT + (size_t)(it.drow0 + n) * it.K + it.k0 + 8 * c), __builtin_bit_cast(f32x4, o)); }
;     LDS_WAIT(); asm volatile("" ::: "memory");
; __device__ __forceinline__ void p0_convert(const Frame& F, const Args& a, int it_lo, int it_hi, int widx, int nw, LAS float* scr) {
;     ...
;             if (more) { cur = nxt;
; #pragma unroll
;                 for (int i = 0; i < 8; ++i) vc[i] = vn[i]; }
.LBB0_1291:
	ds_read2_b32 v[42:43], v88 offset1:36
	s_waitcnt lgkmcnt(1)
	ds_read_b128 v[34:37], v87 offset:9344
	ds_read_b128 v[38:41], v87 offset:9360
	ds_read2_b32 v[44:45], v88 offset0:72 offset1:108
	ds_read2_b32 v[46:47], v88 offset0:144 offset1:180
	ds_read2_b32 v[48:49], v88 offset0:216 offset1:252
	s_waitcnt lgkmcnt(4)
	v_pk_mul_f32 v[42:43], v[34:35], v[42:43]
	s_ashr_i32 s17, s16, 31
	s_waitcnt lgkmcnt(2)
	v_pk_mul_f32 v[44:45], v[36:37], v[44:45]
	v_cvt_pk_bf16_f32 v42, v42, v43
	v_cvt_pk_bf16_f32 v43, v44, v45
	s_waitcnt lgkmcnt(1)
	v_pk_mul_f32 v[44:45], v[38:39], v[46:47]
	s_waitcnt lgkmcnt(0)
	v_pk_mul_f32 v[46:47], v[40:41], v[48:49]
	v_cvt_pk_bf16_f32 v44, v44, v45
	v_cvt_pk_bf16_f32 v45, v46, v47
	v_add_u32_e32 v46, s14, v70
	v_ashrrev_i32_e32 v49, 31, v46
	v_mad_u64_u32 v[46:47], s[0:1], v46, s2, 0
	v_mov_b32_e32 v48, v47
	v_mad_u64_u32 v[48:49], s[0:1], v49, s2, v[48:49]
	v_mov_b32_e32 v47, v48
	v_lshl_add_u64 v[46:47], v[46:47], 1, s[12:13]
	s_lshl_b64 s[16:17], s[16:17], 1
	v_lshl_add_u64 v[46:47], v[46:47], 0, s[16:17]
	v_lshl_add_u64 v[46:47], v[46:47], 0, v[0:1]
	global_store_dwordx4 v[46:47], v[42:45], off sc1
	s_nop 1
	ds_read2_b32 v[42:43], v88 offset0:8 offset1:44
	ds_read2_b32 v[44:45], v88 offset0:80 offset1:116
	v_add_u32_e32 v50, 0x200, v88
	ds_read2_b32 v[46:47], v88 offset0:152 offset1:188
	ds_read2_b32 v[48:49], v50 offset0:96 offset1:132
	s_waitcnt lgkmcnt(3)
	v_pk_mul_f32 v[42:43], v[34:35], v[42:43]
	s_waitcnt lgkmcnt(2)
	v_pk_mul_f32 v[44:45], v[36:37], v[44:45]
	v_cvt_pk_bf16_f32 v42, v42, v43
	v_cvt_pk_bf16_f32 v43, v44, v45
	s_waitcnt lgkmcnt(1)
	v_pk_mul_f32 v[44:45], v[38:39], v[46:47]
	s_waitcnt lgkmcnt(0)
	v_pk_mul_f32 v[46:47], v[40:41], v[48:49]
	v_cvt_pk_bf16_f32 v44, v44, v45
	v_cvt_pk_bf16_f32 v45, v46, v47
	v_add_u32_e32 v46, s14, v71
	v_ashrrev_i32_e32 v49, 31, v46
	v_mad_u64_u32 v[46:47], s[0:1], v46, s2, 0
	v_mov_b32_e32 v48, v47
	v_mad_u64_u32 v[48:49], s[0:1], v49, s2, v[48:49]
	v_mov_b32_e32 v47, v48
	v_lshl_add_u64 v[46:47], v[46:47], 1, s[12:13]
	v_lshl_add_u64 v[46:47], v[46:47], 0, s[16:17]
	v_lshl_add_u64 v[46:47], v[46:47], 0, v[0:1]
	global_store_dwordx4 v[46:47], v[42:45], off sc1
	s_nop 1
	ds_read2_b32 v[42:43], v88 offset0:16 offset1:52
	ds_read2_b32 v[44:45], v88 offset0:88 offset1:124
	ds_read2_b32 v[46:47], v88 offset0:160 offset1:196
	ds_read2_b32 v[48:49], v50 offset0:104 offset1:140
	s_andn2_b64 vcc, exec, s[34:35]
	s_waitcnt lgkmcnt(3)
	v_pk_mul_f32 v[42:43], v[34:35], v[42:43]
	s_waitcnt lgkmcnt(2)
	v_pk_mul_f32 v[44:45], v[36:37], v[44:45]
	v_cvt_pk_bf16_f32 v42, v42, v43
	v_cvt_pk_bf16_f32 v43, v44, v45
	s_waitcnt lgkmcnt(1)
	v_pk_mul_f32 v[44:45], v[38:39], v[46:47]
	s_waitcnt lgkmcnt(0)
	v_pk_mul_f32 v[46:47], v[40:41], v[48:49]
	v_cvt_pk_bf16_f32 v44, v44, v45
	v_cvt_pk_bf16_f32 v45, v46, v47
	v_add_u32_e32 v46, s14, v72
	v_ashrrev_i32_e32 v49, 31, v46
	v_mad_u64_u32 v[46:47], s[0:1], v46, s2, 0
	v_mov_b32_e32 v48, v47
	v_mad_u64_u32 v[48:49], s[0:1], v49, s2, v[48:49]
	v_mov_b32_e32 v47, v48
	v_lshl_add_u64 v[46:47], v[46:47], 1, s[12:13]
	v_lshl_add_u64 v[46:47], v[46:47], 0, s[16:17]
	v_lshl_add_u64 v[46:47], v[46:47], 0, v[0:1]
	global_store_dwordx4 v[46:47], v[42:45], off sc1
	s_nop 1
	ds_read2_b32 v[42:43], v88 offset0:24 offset1:60
	ds_read2_b32 v[44:45], v88 offset0:96 offset1:132
	ds_read2_b32 v[46:47], v50 offset0:112 offset1:148
	s_waitcnt lgkmcnt(2)
	v_pk_mul_f32 v[34:35], v[34:35], v[42:43]
	ds_read2_b32 v[42:43], v88 offset0:168 offset1:204
	s_waitcnt lgkmcnt(2)
	v_pk_mul_f32 v[36:37], v[36:37], v[44:45]
	v_cvt_pk_bf16_f32 v34, v34, v35
	v_cvt_pk_bf16_f32 v35, v36, v37
	s_waitcnt lgkmcnt(0)
	v_pk_mul_f32 v[36:37], v[38:39], v[42:43]
	v_pk_mul_f32 v[38:39], v[40:41], v[46:47]
	v_cvt_pk_bf16_f32 v36, v36, v37
	v_cvt_pk_bf16_f32 v37, v38, v39
	v_add_u32_e32 v38, s14, v73
	v_ashrrev_i32_e32 v41, 31, v38
	v_mad_u64_u32 v[38:39], s[0:1], v38, s2, 0
	v_mov_b32_e32 v40, v39
	v_mad_u64_u32 v[40:41], s[0:1], v41, s2, v[40:41]
	v_mov_b32_e32 v39, v40
	v_lshl_add_u64 v[38:39], v[38:39], 1, s[12:13]
	v_lshl_add_u64 v[38:39], v[38:39], 0, s[16:17]
	v_lshl_add_u64 v[38:39], v[38:39], 0, v[0:1]
	global_store_dwordx4 v[38:39], v[34:37], off sc1
	s_nop 1
	s_waitcnt lgkmcnt(0)
	s_mov_b64 s[12:13], -1
	s_cbranch_vccnz .LBB0_1259
	s_waitcnt vmcnt(4)
	s_mov_b64 s[12:13], 0
	v_mov_b32_e32 v49, v33
	v_mov_b32_e32 v48, v32
	v_mov_b32_e32 v47, v31
	v_mov_b32_e32 v46, v30
	v_mov_b32_e32 v37, v21
	v_mov_b32_e32 v36, v20
	v_mov_b32_e32 v35, v19
	v_mov_b32_e32 v34, v18
	v_mov_b32_e32 v53, v25
	v_mov_b32_e32 v52, v24
	v_mov_b32_e32 v51, v23
	v_mov_b32_e32 v50, v22
	v_mov_b32_e32 v41, v13
	v_mov_b32_e32 v40, v12
	v_mov_b32_e32 v39, v11
	v_mov_b32_e32 v38, v10
	v_mov_b32_e32 v57, v17
	v_mov_b32_e32 v56, v16
	v_mov_b32_e32 v55, v15
	v_mov_b32_e32 v54, v14
	v_mov_b32_e32 v45, v5
	v_mov_b32_e32 v44, v4
	v_mov_b32_e32 v43, v3
	v_mov_b32_e32 v42, v2
	v_mov_b32_e32 v61, v9
	v_mov_b32_e32 v60, v8
	v_mov_b32_e32 v59, v7
	v_mov_b32_e32 v58, v6
	s_branch .LBB0_1259
.Lcv_np_fu0:
	s_waitcnt vmcnt(0)
	s_branch .LBB0_1278
.LBB0_1293:
	s_movk_i32 s40, 0xb00
	s_mov_b64 s[62:63], 0x400
	s_mov_b64 s[26:27], 0
	s_mov_b64 s[24:25], 0
	s_mov_b64 s[30:31], 0
	s_mov_b32 s48, s41
	s_mov_b64 s[60:61], 0
	s_andn2_b64 vcc, exec, s[88:89]
	s_cbranch_vccz .LBB0_1268
	s_branch .LBB0_1269

; __device__ __forceinline__ void p0_item_process(const PItem& it, int lane, const f32x4 (&v)[8], LAS float* scr) {
;     ...
;     gl[lane] = it.g ? it.g[it.k0 + lane] : 1.f; bl[lane] = it.be ? it.be[it.k0 + lane] : 0.f;
.Lcv_ng_fu1:
	s_cmp_eq_u64 s[86:87], 0
	s_cbranch_scc1 .Lcv_nb_fu1
	v_lshl_add_u64 v[234:235], v[232:233], 2, s[86:87]
	global_load_dword v231, v[234:235], off

; #define LAS __attribute__((address_space(3)))
; #define LDS_WAIT() asm volatile("s_waitcnt lgkmcnt(0)" ::: "memory")
; __device__ __forceinline__ void p0_item_process(const PItem& it, int lane, const f32x4 (&v)[8], LAS float* scr) {
;     LAS float* gl = scr + 64 * 36 + 32; LAS float* bl = gl + 64;
;     ...
; #pragma unroll
;     for (int i = 0; i < 8; ++i) *(LAS f32x4*)(scr + SCR_ROW(8 * i + (lane >> 3)) + 4 * (lane & 7)) = v[i];
;     gl[lane] = it.g ? it.g[it.k0 + lane] : 1.f; bl[lane] = it.be ? it.be[it.k0 + lane] : 0.f;
;     LDS_WAIT(); asm volatile("" ::: "memory");
.LBB0_1332:
	s_waitcnt vmcnt(15)
	ds_write_b128 v78, v[58:61]
	s_waitcnt vmcnt(14)
	ds_write_b128 v79, v[42:45] offset:16
	s_waitcnt vmcnt(13)
	ds_write_b128 v80, v[54:57] offset:32
	s_waitcnt vmcnt(12)
	ds_write_b128 v81, v[38:41] offset:48
	s_waitcnt vmcnt(11)
	ds_write_b128 v82, v[50:53] offset:64
	s_waitcnt vmcnt(10)
	ds_write_b128 v83, v[34:37] offset:80
	s_waitcnt vmcnt(9)
	ds_write_b128 v84, v[46:49] offset:96
	s_waitcnt vmcnt(8)
	ds_write_b128 v85, v[62:65] offset:112
	s_cmp_lg_u64 s[86:87], 0
	s_cselect_b64 s[24:25], -1, 0
	s_waitcnt vmcnt(8)
	ds_write_b32 v86, v230 offset:9344
	ds_write_b32 v86, v231 offset:9600
	s_waitcnt lgkmcnt(0)
	s_cmp_eq_u64 s[20:21], 0
	s_cbranch_scc1 .LBB0_1345
	v_mov_b32_e32 v34, 0
	s_mov_b32 s0, 0
	v_mov_b32_e32 v36, v90
	v_mov_b32_e32 v35, v34

; __device__ __forceinline__ PItem p0_decode(const Args& a, int it) {
;     ...
;     { const int kb = r / 32, nb = r % 32; p.W = a.in[18] + (size_t)l * DFF * D; p.N = D; p.K = DFF; p.g = nullptr; p.be = nullptr; p.WT = (bf16*)(wl + W_2); p.drow0 = 32 * nb; p.k0 = 64 * kb; p.n0 = 32 * nb; p.c1 = nullptr; p.c2 = nullptr; return p; }
; __device__ __forceinline__ void p0_convert(const Frame& F, const Args& a, int it_lo, int it_hi, int widx, int nw, LAS float* scr) {
;     ...
;         for (int it = it0; it < itend; it += nw) {
;             const bool more = it + nw < itend;
;             PItem nxt = cur; f32x4 vn[8];
;             if (more) { nxt = p0_decode(a, it + nw); p0_item_load(nxt, F.lane, vn); }
;             p0_item_process(cur, F.lane, vc, scr);
;             if (more) { cur = nxt;
; #pragma unroll
;                 for (int i = 0; i < 8; ++i) vc[i] = vn[i]; }
.Lcv_np_fu1:
	s_waitcnt vmcnt(0)
	s_branch .LBB0_1332
.LBB0_1347:
	s_movk_i32 s2, 0xb00
	s_mov_b64 s[48:49], 0x400
	s_mov_b64 s[30:31], 0
	s_mov_b64 s[64:65], 0
	s_mov_b64 s[26:27], 0
	s_mov_b32 s62, s52
	s_mov_b64 s[56:57], 0
	s_andn2_b64 vcc, exec, s[90:91]
	s_cbranch_vccz .LBB0_1322
	s_branch .LBB0_1323
